# out-proj GEMM K-loop also restructured to 4 phases of 32 MFMA per barrier pair (same re-derived stage schedule as the in-proj loop)
# speedup vs baseline: 1.0248x; 1.0072x over previous
.LBB0_482:
	s_lshl_b32 s1, s1, 5
	s_and_b32 s1, s1, 0x60
	s_lshl_b32 s12, s0, 13
	s_lshl_b32 s13, s1, 7
	v_readlane_b32 s14, v253, 40
	s_add_u32 s6, s10, s14
	s_addc_u32 s7, s11, 0
	s_add_i32 s74, s41, 0x18000
	v_mov_b32_e32 v129, v145
	v_lshl_add_u64 v[2:3], s[6:7], 0, v[144:145]
	s_mov_b32 m0, s74
	s_waitcnt vmcnt(4)
	s_barrier
	global_load_lds_dwordx4 v[2:3], off
	v_lshl_add_u64 v[2:3], s[6:7], 0, v[128:129]
	s_add_i32 s75, s41, 0x1a000
	v_readlane_b32 s6, v253, 43
	v_mov_b32_e32 v133, v145
	s_mov_b32 m0, s75
	v_readlane_b32 s7, v253, 44
	s_add_i32 s76, s41, 0x8000
	s_add_i32 s77, s41, 0xa000
	v_mov_b32_e32 v131, v145
	global_load_lds_dwordx4 v[2:3], off
	v_lshl_add_u64 v[2:3], s[6:7], 0, v[132:133]
	s_mov_b32 m0, s76
	s_add_u32 s4, s4, s14
	global_load_lds_dwordx4 v[2:3], off
	v_lshl_add_u64 v[2:3], s[6:7], 0, v[130:131]
	s_mov_b32 m0, s77
	s_addc_u32 s5, s5, 0
	s_add_i32 s78, s41, 0x1c000
	global_load_lds_dwordx4 v[2:3], off
	v_lshl_add_u64 v[2:3], s[4:5], 0, v[144:145]
	s_mov_b32 m0, s78
	s_add_i32 s79, s41, 0x1e000
	global_load_lds_dwordx4 v[2:3], off
	v_lshl_add_u64 v[2:3], s[4:5], 0, v[128:129]
	s_mov_b32 m0, s79
	v_and_b32_e32 v1, 15, v0
	global_load_lds_dwordx4 v[2:3], off
	v_lshrrev_b32_e32 v2, 1, v0
	v_and_b32_e32 v2, 24, v2
	v_lshlrev_b32_e32 v3, 1, v2
	v_lshlrev_b32_e32 v0, 2, v0
	v_lshl_or_b32 v138, s0, 6, v1
	v_lshl_or_b32 v1, v1, 6, v3
	v_and_b32_e32 v0, 32, v0
	s_waitcnt vmcnt(6)
	v_bitop3_b32 v139, v1, s12, v0 bitop3:0xde
	v_bitop3_b32 v140, v1, s13, v0 bitop3:0xde
	v_readlane_b32 s12, v253, 41
	v_or_b32_e32 v141, s1, v2
	s_mov_b32 s80, 0
	v_readlane_b32 s83, v253, 31
	v_readlane_b32 s84, v253, 32
	v_readlane_b32 s13, v253, 42
	s_barrier
	s_barrier

.LBB0_494:
	s_cmpk_eq_i32 s85, 0xf80
	s_cselect_b32 s37, s5, s13
	s_cselect_b32 s36, s4, s12
	s_cselect_b32 s88, s7, s11
	s_cselect_b32 s89, s6, s10
	s_add_i32 s14, s86, 3
	s_cmpk_eq_i32 s85, 0xf80
	s_cselect_b32 s14, 1, s14
	s_add_i32 s87, s86, 2
	s_cmpk_eq_i32 s85, 0xf80
	s_cselect_b32 s15, 0, s87
	s_add_i32 s15, s15, s64
	s_add_i32 s14, s14, s64
	s_add_i32 s38, s66, s85
	s_lshl_b32 s15, s15, 7
	s_lshl_b32 s14, s14, 7
	s_and_b32 s91, s38, 0xf80
	s_and_b32 s92, s15, 0xf80
	s_and_b32 s90, s14, 0xf80
	s_add_u32 s38, s89, s92
	s_addc_u32 s39, s88, 0
	s_add_u32 s36, s36, s92
	s_addc_u32 s37, s37, 0
	s_add_u32 s14, s10, s91
	s_addc_u32 s15, s11, 0
	s_add_u32 s14, s14, 0x84000
	s_addc_u32 s15, s15, 0
	s_add_u32 s92, s12, s91
	s_addc_u32 s93, s13, 0
	v_add_u32_e32 v222, 0x10000, v140
	ds_read_b128 v[134:137], v222
	ds_read_b128 v[148:151], v222 offset:1024
	ds_read_b128 v[152:155], v222 offset:2048
	ds_read_b128 v[156:159], v222 offset:3072
	v_add_u32_e32 v223, 0x14000, v140
	ds_read_b128 v[204:207], v223
	ds_read_b128 v[208:211], v223 offset:1024
	ds_read_b128 v[212:215], v223 offset:2048
	ds_read_b128 v[216:219], v223 offset:3072
	ds_read_b128 v[160:163], v139
	ds_read_b128 v[164:167], v139 offset:1024
	ds_read_b128 v[168:171], v139 offset:2048
	ds_read_b128 v[172:175], v139 offset:3072
	v_lshl_add_u64 v[220:221], s[92:93], 0, v[132:133]
	s_mov_b32 m0, s76
	s_nop 0
	global_load_lds_dwordx4 v[220:221], off
	v_lshl_add_u64 v[220:221], s[92:93], 0, v[130:131]
	s_mov_b32 m0, s77
	s_nop 0
	global_load_lds_dwordx4 v[220:221], off
	v_lshl_add_u64 v[220:221], s[14:15], 0, v[144:145]
	s_mov_b32 m0, s78
	s_nop 0
	global_load_lds_dwordx4 v[220:221], off
	v_lshl_add_u64 v[220:221], s[14:15], 0, v[128:129]
	s_mov_b32 m0, s79
	s_nop 0
	global_load_lds_dwordx4 v[220:221], off
	s_waitcnt lgkmcnt(11)
	ds_read_b128 v[188:191], v139 offset:4096
	ds_read_b128 v[192:195], v139 offset:5120
	ds_read_b128 v[196:199], v139 offset:6144
	ds_read_b128 v[200:203], v139 offset:7168
	s_waitcnt vmcnt(6)
	s_waitcnt lgkmcnt(8)
	s_barrier
	s_waitcnt lgkmcnt(0)
	s_setprio 1
	v_mfma_f32_16x16x32_bf16 v[124:127], v[134:137], v[160:163], v[124:127]
	v_mfma_f32_16x16x32_bf16 v[120:123], v[152:155], v[160:163], v[120:123]
	v_mfma_f32_16x16x32_bf16 v[116:119], v[134:137], v[168:171], v[116:119]
	v_mfma_f32_16x16x32_bf16 v[108:111], v[152:155], v[168:171], v[108:111]
	v_mfma_f32_16x16x32_bf16 v[100:103], v[134:137], v[188:191], v[100:103]
	v_mfma_f32_16x16x32_bf16 v[92:95], v[152:155], v[188:191], v[92:95]
	v_mfma_f32_16x16x32_bf16 v[84:87], v[134:137], v[196:199], v[84:87]
	v_mfma_f32_16x16x32_bf16 v[76:79], v[152:155], v[196:199], v[76:79]
	v_mfma_f32_16x16x32_bf16 v[124:127], v[148:151], v[164:167], v[124:127]
	v_mfma_f32_16x16x32_bf16 v[120:123], v[156:159], v[164:167], v[120:123]
	v_mfma_f32_16x16x32_bf16 v[116:119], v[148:151], v[172:175], v[116:119]
	v_mfma_f32_16x16x32_bf16 v[108:111], v[156:159], v[172:175], v[108:111]
	v_mfma_f32_16x16x32_bf16 v[100:103], v[148:151], v[192:195], v[100:103]
	v_mfma_f32_16x16x32_bf16 v[92:95], v[156:159], v[192:195], v[92:95]
	v_mfma_f32_16x16x32_bf16 v[84:87], v[148:151], v[200:203], v[84:87]
	v_mfma_f32_16x16x32_bf16 v[76:79], v[156:159], v[200:203], v[76:79]
	v_mfma_f32_16x16x32_bf16 v[112:115], v[204:207], v[160:163], v[112:115]
	v_mfma_f32_16x16x32_bf16 v[104:107], v[212:215], v[160:163], v[104:107]
	v_mfma_f32_16x16x32_bf16 v[96:99], v[204:207], v[168:171], v[96:99]
	v_mfma_f32_16x16x32_bf16 v[88:91], v[212:215], v[168:171], v[88:91]
	v_mfma_f32_16x16x32_bf16 v[80:83], v[204:207], v[188:191], v[80:83]
	v_mfma_f32_16x16x32_bf16 v[72:75], v[212:215], v[188:191], v[72:75]
	v_mfma_f32_16x16x32_bf16 v[68:71], v[204:207], v[196:199], v[68:71]
	v_mfma_f32_16x16x32_bf16 v[64:67], v[212:215], v[196:199], v[64:67]
	v_mfma_f32_16x16x32_bf16 v[112:115], v[208:211], v[164:167], v[112:115]
	v_mfma_f32_16x16x32_bf16 v[104:107], v[216:219], v[164:167], v[104:107]
	v_mfma_f32_16x16x32_bf16 v[96:99], v[208:211], v[172:175], v[96:99]
	v_mfma_f32_16x16x32_bf16 v[88:91], v[216:219], v[172:175], v[88:91]
	v_mfma_f32_16x16x32_bf16 v[80:83], v[208:211], v[192:195], v[80:83]
	v_mfma_f32_16x16x32_bf16 v[72:75], v[216:219], v[192:195], v[72:75]
	v_mfma_f32_16x16x32_bf16 v[68:71], v[208:211], v[200:203], v[68:71]
	v_mfma_f32_16x16x32_bf16 v[64:67], v[216:219], v[200:203], v[64:67]
	s_setprio 0
	s_barrier
	ds_read_b128 v[160:163], v139 offset:16384
	ds_read_b128 v[164:167], v139 offset:17408
	ds_read_b128 v[168:171], v139 offset:18432
	ds_read_b128 v[172:175], v139 offset:19456
	ds_read_b128 v[188:191], v139 offset:20480
	ds_read_b128 v[192:195], v139 offset:21504
	ds_read_b128 v[196:199], v139 offset:22528
	ds_read_b128 v[200:203], v139 offset:23552
	s_add_u32 s92, s92, 0x84000
	s_addc_u32 s93, s93, 0
	v_lshl_add_u64 v[220:221], s[92:93], 0, v[132:133]
	s_add_i32 m0, s41, 0xc000
	s_nop 0
	global_load_lds_dwordx4 v[220:221], off
	v_lshl_add_u64 v[220:221], s[92:93], 0, v[130:131]
	s_add_i32 m0, s41, 0xe000
	s_nop 0
	global_load_lds_dwordx4 v[220:221], off
	v_lshl_add_u64 v[220:221], s[38:39], 0, v[144:145]
	s_mov_b32 m0, s44
	s_nop 0
	global_load_lds_dwordx4 v[220:221], off
	v_lshl_add_u64 v[220:221], s[38:39], 0, v[128:129]
	s_mov_b32 m0, s45
	s_nop 0
	global_load_lds_dwordx4 v[220:221], off
	s_waitcnt vmcnt(4)
	s_barrier
	s_waitcnt lgkmcnt(0)
	s_setprio 1
	v_mfma_f32_16x16x32_bf16 v[60:63], v[134:137], v[160:163], v[60:63]
	v_mfma_f32_16x16x32_bf16 v[56:59], v[152:155], v[160:163], v[56:59]
	v_mfma_f32_16x16x32_bf16 v[52:55], v[134:137], v[168:171], v[52:55]
	v_mfma_f32_16x16x32_bf16 v[44:47], v[152:155], v[168:171], v[44:47]
	v_mfma_f32_16x16x32_bf16 v[36:39], v[134:137], v[188:191], v[36:39]
	v_mfma_f32_16x16x32_bf16 v[28:31], v[152:155], v[188:191], v[28:31]
	v_mfma_f32_16x16x32_bf16 v[20:23], v[134:137], v[196:199], v[20:23]
	v_mfma_f32_16x16x32_bf16 v[12:15], v[152:155], v[196:199], v[12:15]
	v_mfma_f32_16x16x32_bf16 v[60:63], v[148:151], v[164:167], v[60:63]
	v_mfma_f32_16x16x32_bf16 v[56:59], v[156:159], v[164:167], v[56:59]
	v_mfma_f32_16x16x32_bf16 v[52:55], v[148:151], v[172:175], v[52:55]
	v_mfma_f32_16x16x32_bf16 v[44:47], v[156:159], v[172:175], v[44:47]
	v_mfma_f32_16x16x32_bf16 v[36:39], v[148:151], v[192:195], v[36:39]
	v_mfma_f32_16x16x32_bf16 v[28:31], v[156:159], v[192:195], v[28:31]
	v_mfma_f32_16x16x32_bf16 v[20:23], v[148:151], v[200:203], v[20:23]
	v_mfma_f32_16x16x32_bf16 v[12:15], v[156:159], v[200:203], v[12:15]
	v_mfma_f32_16x16x32_bf16 v[48:51], v[204:207], v[160:163], v[48:51]
	v_mfma_f32_16x16x32_bf16 v[40:43], v[212:215], v[160:163], v[40:43]
	v_mfma_f32_16x16x32_bf16 v[32:35], v[204:207], v[168:171], v[32:35]
	v_mfma_f32_16x16x32_bf16 v[24:27], v[212:215], v[168:171], v[24:27]
	v_mfma_f32_16x16x32_bf16 v[16:19], v[204:207], v[188:191], v[16:19]
	v_mfma_f32_16x16x32_bf16 v[8:11], v[212:215], v[188:191], v[8:11]
	v_mfma_f32_16x16x32_bf16 v[4:7], v[204:207], v[196:199], v[4:7]
	v_mfma_f32_16x16x32_bf16 v[0:3], v[212:215], v[196:199], v[0:3]
	v_mfma_f32_16x16x32_bf16 v[48:51], v[208:211], v[164:167], v[48:51]
	v_mfma_f32_16x16x32_bf16 v[40:43], v[216:219], v[164:167], v[40:43]
	v_mfma_f32_16x16x32_bf16 v[32:35], v[208:211], v[172:175], v[32:35]
	v_mfma_f32_16x16x32_bf16 v[24:27], v[216:219], v[172:175], v[24:27]
	v_mfma_f32_16x16x32_bf16 v[16:19], v[208:211], v[192:195], v[16:19]
	v_mfma_f32_16x16x32_bf16 v[8:11], v[216:219], v[192:195], v[8:11]
	v_mfma_f32_16x16x32_bf16 v[4:7], v[208:211], v[200:203], v[4:7]
	v_mfma_f32_16x16x32_bf16 v[0:3], v[216:219], v[200:203], v[0:3]
	s_setprio 0
	s_barrier
	v_add_u32_e32 v222, 0x18000, v140
	ds_read_b128 v[134:137], v222
	ds_read_b128 v[148:151], v222 offset:1024
	ds_read_b128 v[152:155], v222 offset:2048
	ds_read_b128 v[156:159], v222 offset:3072
	v_add_u32_e32 v223, 0x1c000, v140
	ds_read_b128 v[204:207], v223
	ds_read_b128 v[208:211], v223 offset:1024
	ds_read_b128 v[212:215], v223 offset:2048
	ds_read_b128 v[216:219], v223 offset:3072
	ds_read_b128 v[160:163], v139 offset:32768
	ds_read_b128 v[164:167], v139 offset:33792
	ds_read_b128 v[168:171], v139 offset:34816
	ds_read_b128 v[172:175], v139 offset:35840
	v_lshl_add_u64 v[220:221], s[36:37], 0, v[132:133]
	s_mov_b32 m0, s41
	s_nop 0
	global_load_lds_dwordx4 v[220:221], off
	v_lshl_add_u64 v[220:221], s[36:37], 0, v[130:131]
	s_mov_b32 m0, s59
	s_nop 0
	global_load_lds_dwordx4 v[220:221], off
	s_add_u32 s38, s38, 0x84000
	s_addc_u32 s39, s39, 0
	v_lshl_add_u64 v[220:221], s[38:39], 0, v[144:145]
	s_mov_b32 m0, s60
	s_nop 0
	global_load_lds_dwordx4 v[220:221], off
	v_lshl_add_u64 v[220:221], s[38:39], 0, v[128:129]
	s_mov_b32 m0, s61
	s_nop 0
	global_load_lds_dwordx4 v[220:221], off
	s_waitcnt lgkmcnt(11)
	ds_read_b128 v[188:191], v139 offset:36864
	ds_read_b128 v[192:195], v139 offset:37888
	ds_read_b128 v[196:199], v139 offset:38912
	ds_read_b128 v[200:203], v139 offset:39936
	s_waitcnt vmcnt(6)
	s_waitcnt lgkmcnt(8)
	s_barrier
	s_waitcnt lgkmcnt(0)
	s_setprio 1
	v_mfma_f32_16x16x32_bf16 v[124:127], v[134:137], v[160:163], v[124:127]
	v_mfma_f32_16x16x32_bf16 v[120:123], v[152:155], v[160:163], v[120:123]
	v_mfma_f32_16x16x32_bf16 v[116:119], v[134:137], v[168:171], v[116:119]
	v_mfma_f32_16x16x32_bf16 v[108:111], v[152:155], v[168:171], v[108:111]
	v_mfma_f32_16x16x32_bf16 v[100:103], v[134:137], v[188:191], v[100:103]
	v_mfma_f32_16x16x32_bf16 v[92:95], v[152:155], v[188:191], v[92:95]
	v_mfma_f32_16x16x32_bf16 v[84:87], v[134:137], v[196:199], v[84:87]
	v_mfma_f32_16x16x32_bf16 v[76:79], v[152:155], v[196:199], v[76:79]
	v_mfma_f32_16x16x32_bf16 v[124:127], v[148:151], v[164:167], v[124:127]
	v_mfma_f32_16x16x32_bf16 v[120:123], v[156:159], v[164:167], v[120:123]
	v_mfma_f32_16x16x32_bf16 v[116:119], v[148:151], v[172:175], v[116:119]
	v_mfma_f32_16x16x32_bf16 v[108:111], v[156:159], v[172:175], v[108:111]
	v_mfma_f32_16x16x32_bf16 v[100:103], v[148:151], v[192:195], v[100:103]
	v_mfma_f32_16x16x32_bf16 v[92:95], v[156:159], v[192:195], v[92:95]
	v_mfma_f32_16x16x32_bf16 v[84:87], v[148:151], v[200:203], v[84:87]
	v_mfma_f32_16x16x32_bf16 v[76:79], v[156:159], v[200:203], v[76:79]
	v_mfma_f32_16x16x32_bf16 v[112:115], v[204:207], v[160:163], v[112:115]
	v_mfma_f32_16x16x32_bf16 v[104:107], v[212:215], v[160:163], v[104:107]
	v_mfma_f32_16x16x32_bf16 v[96:99], v[204:207], v[168:171], v[96:99]
	v_mfma_f32_16x16x32_bf16 v[88:91], v[212:215], v[168:171], v[88:91]
	v_mfma_f32_16x16x32_bf16 v[80:83], v[204:207], v[188:191], v[80:83]
	v_mfma_f32_16x16x32_bf16 v[72:75], v[212:215], v[188:191], v[72:75]
	v_mfma_f32_16x16x32_bf16 v[68:71], v[204:207], v[196:199], v[68:71]
	v_mfma_f32_16x16x32_bf16 v[64:67], v[212:215], v[196:199], v[64:67]
	v_mfma_f32_16x16x32_bf16 v[112:115], v[208:211], v[164:167], v[112:115]
	v_mfma_f32_16x16x32_bf16 v[104:107], v[216:219], v[164:167], v[104:107]
	v_mfma_f32_16x16x32_bf16 v[96:99], v[208:211], v[172:175], v[96:99]
	v_mfma_f32_16x16x32_bf16 v[88:91], v[216:219], v[172:175], v[88:91]
	v_mfma_f32_16x16x32_bf16 v[80:83], v[208:211], v[192:195], v[80:83]
	v_mfma_f32_16x16x32_bf16 v[72:75], v[216:219], v[192:195], v[72:75]
	v_mfma_f32_16x16x32_bf16 v[68:71], v[208:211], v[200:203], v[68:71]
	v_mfma_f32_16x16x32_bf16 v[64:67], v[216:219], v[200:203], v[64:67]
	s_setprio 0
	s_barrier
	ds_read_b128 v[160:163], v139 offset:49152
	ds_read_b128 v[164:167], v139 offset:50176
	ds_read_b128 v[168:171], v139 offset:51200
	ds_read_b128 v[172:175], v139 offset:52224
	ds_read_b128 v[188:191], v139 offset:53248
	ds_read_b128 v[192:195], v139 offset:54272
	ds_read_b128 v[196:199], v139 offset:55296
	ds_read_b128 v[200:203], v139 offset:56320
	s_add_u32 s36, s36, 0x84000
	s_addc_u32 s37, s37, 0
	v_lshl_add_u64 v[220:221], s[36:37], 0, v[132:133]
	s_mov_b32 m0, s62
	s_nop 0
	global_load_lds_dwordx4 v[220:221], off
	v_lshl_add_u64 v[220:221], s[36:37], 0, v[130:131]
	s_mov_b32 m0, s63
	s_nop 0
	global_load_lds_dwordx4 v[220:221], off
	s_add_u32 s14, s89, s90
	s_addc_u32 s15, s88, 0
	v_lshl_add_u64 v[220:221], s[14:15], 0, v[144:145]
	s_mov_b32 m0, s74
	s_nop 0
	global_load_lds_dwordx4 v[220:221], off
	v_lshl_add_u64 v[220:221], s[14:15], 0, v[128:129]
	s_mov_b32 m0, s75
	s_nop 0
	global_load_lds_dwordx4 v[220:221], off
	s_waitcnt vmcnt(4)
	s_barrier
	s_waitcnt lgkmcnt(0)
	s_setprio 1
	v_mfma_f32_16x16x32_bf16 v[60:63], v[134:137], v[160:163], v[60:63]
	v_mfma_f32_16x16x32_bf16 v[56:59], v[152:155], v[160:163], v[56:59]
	v_mfma_f32_16x16x32_bf16 v[52:55], v[134:137], v[168:171], v[52:55]
	v_mfma_f32_16x16x32_bf16 v[44:47], v[152:155], v[168:171], v[44:47]
	v_mfma_f32_16x16x32_bf16 v[36:39], v[134:137], v[188:191], v[36:39]
	v_mfma_f32_16x16x32_bf16 v[28:31], v[152:155], v[188:191], v[28:31]
	v_mfma_f32_16x16x32_bf16 v[20:23], v[134:137], v[196:199], v[20:23]
	v_mfma_f32_16x16x32_bf16 v[12:15], v[152:155], v[196:199], v[12:15]
	v_mfma_f32_16x16x32_bf16 v[60:63], v[148:151], v[164:167], v[60:63]
	v_mfma_f32_16x16x32_bf16 v[56:59], v[156:159], v[164:167], v[56:59]
	v_mfma_f32_16x16x32_bf16 v[52:55], v[148:151], v[172:175], v[52:55]
	v_mfma_f32_16x16x32_bf16 v[44:47], v[156:159], v[172:175], v[44:47]
	v_mfma_f32_16x16x32_bf16 v[36:39], v[148:151], v[192:195], v[36:39]
	v_mfma_f32_16x16x32_bf16 v[28:31], v[156:159], v[192:195], v[28:31]
	v_mfma_f32_16x16x32_bf16 v[20:23], v[148:151], v[200:203], v[20:23]
	v_mfma_f32_16x16x32_bf16 v[12:15], v[156:159], v[200:203], v[12:15]
	v_mfma_f32_16x16x32_bf16 v[48:51], v[204:207], v[160:163], v[48:51]
	v_mfma_f32_16x16x32_bf16 v[40:43], v[212:215], v[160:163], v[40:43]
	v_mfma_f32_16x16x32_bf16 v[32:35], v[204:207], v[168:171], v[32:35]
	v_mfma_f32_16x16x32_bf16 v[24:27], v[212:215], v[168:171], v[24:27]
	v_mfma_f32_16x16x32_bf16 v[16:19], v[204:207], v[188:191], v[16:19]
	v_mfma_f32_16x16x32_bf16 v[8:11], v[212:215], v[188:191], v[8:11]
	v_mfma_f32_16x16x32_bf16 v[4:7], v[204:207], v[196:199], v[4:7]
	v_mfma_f32_16x16x32_bf16 v[0:3], v[212:215], v[196:199], v[0:3]
	v_mfma_f32_16x16x32_bf16 v[48:51], v[208:211], v[164:167], v[48:51]
	v_mfma_f32_16x16x32_bf16 v[40:43], v[216:219], v[164:167], v[40:43]
	v_mfma_f32_16x16x32_bf16 v[32:35], v[208:211], v[172:175], v[32:35]
	v_mfma_f32_16x16x32_bf16 v[24:27], v[216:219], v[172:175], v[24:27]
	v_mfma_f32_16x16x32_bf16 v[16:19], v[208:211], v[192:195], v[16:19]
	v_mfma_f32_16x16x32_bf16 v[8:11], v[216:219], v[192:195], v[8:11]
	v_mfma_f32_16x16x32_bf16 v[4:7], v[208:211], v[200:203], v[4:7]
	v_mfma_f32_16x16x32_bf16 v[0:3], v[216:219], v[200:203], v[0:3]
	s_setprio 0
	s_addk_i32 s85, 0x100
	s_cmp_gt_u32 s86, 29
	s_mov_b32 s86, s87
	s_barrier
	s_cbranch_scc0 .LBB0_494
	v_readlane_b32 s10, v252, 58
	v_lshl_add_u32 v146, s84, 8, v138
	v_lshl_or_b32 v136, s83, 8, v141
	v_readlane_b32 s11, v252, 59
	v_ashrrev_i32_e32 v137, 31, v136
	v_cvt_pk_bf16_f32 v68, v68, v69
	v_cvt_pk_bf16_f32 v69, v70, v71
	v_cvt_pk_bf16_f32 v70, v64, v65
	v_add_u32_e32 v64, 0x80, v146
	v_mov_b64_e32 v[134:135], s[10:11]
	v_mad_i64_i32 v[142:143], s[10:11], v146, s70, v[134:135]
	v_lshlrev_b64 v[136:137], 1, v[136:137]
	v_cvt_pk_bf16_f32 v112, v112, v113
	v_cvt_pk_bf16_f32 v113, v114, v115
	v_cvt_pk_bf16_f32 v114, v104, v105
	v_or_b32_e32 v104, 16, v146
	v_mad_i64_i32 v[64:65], s[10:11], v64, s70, v[134:135]
	v_cvt_pk_bf16_f32 v48, v48, v49
	v_cvt_pk_bf16_f32 v49, v50, v51
	v_cvt_pk_bf16_f32 v50, v40, v41
	v_add_u32_e32 v40, 0x90, v146
	v_lshl_add_u64 v[142:143], v[142:143], 0, v[136:137]
	v_mad_i64_i32 v[104:105], s[10:11], v104, s70, v[134:135]
	v_cvt_pk_bf16_f32 v96, v96, v97
	v_cvt_pk_bf16_f32 v97, v98, v99
	v_cvt_pk_bf16_f32 v98, v88, v89
	v_or_b32_e32 v88, 32, v146
	v_lshl_add_u64 v[64:65], v[64:65], 0, v[136:137]
	v_mad_i64_i32 v[40:41], s[10:11], v40, s70, v[134:135]
	v_cvt_pk_bf16_f32 v32, v32, v33
	v_cvt_pk_bf16_f32 v33, v34, v35
	v_cvt_pk_bf16_f32 v34, v24, v25
	v_add_u32_e32 v24, 0xa0, v146
	v_cvt_pk_bf16_f32 v115, v106, v107
	global_store_dwordx4 v[142:143], v[112:115], off offset:256
	v_mad_i64_i32 v[88:89], s[10:11], v88, s70, v[134:135]
	s_nop 0
	v_lshl_add_u64 v[112:113], v[104:105], 0, v[136:137]
	v_cvt_pk_bf16_f32 v80, v80, v81
	v_cvt_pk_bf16_f32 v81, v82, v83
	v_cvt_pk_bf16_f32 v82, v72, v73
	v_or_b32_e32 v72, 48, v146
	v_cvt_pk_bf16_f32 v51, v42, v43
	global_store_dwordx4 v[64:65], v[48:51], off offset:256
	v_mad_i64_i32 v[24:25], s[10:11], v24, s70, v[134:135]
	s_nop 0
	v_lshl_add_u64 v[48:49], v[40:41], 0, v[136:137]
	v_cvt_pk_bf16_f32 v16, v16, v17
	v_cvt_pk_bf16_f32 v17, v18, v19
	v_cvt_pk_bf16_f32 v18, v8, v9
	v_add_u32_e32 v8, 0xb0, v146
	v_cvt_pk_bf16_f32 v99, v90, v91
	global_store_dwordx4 v[112:113], v[96:99], off offset:256
	v_mad_i64_i32 v[72:73], s[10:11], v72, s70, v[134:135]
	s_nop 0
	v_lshl_add_u64 v[96:97], v[88:89], 0, v[136:137]
	v_cvt_pk_bf16_f32 v35, v26, v27
	global_store_dwordx4 v[48:49], v[32:35], off offset:256
	v_mad_i64_i32 v[8:9], s[10:11], v8, s70, v[134:135]
	s_nop 0
	v_lshl_add_u64 v[32:33], v[24:25], 0, v[136:137]
	v_cvt_pk_bf16_f32 v83, v74, v75
	global_store_dwordx4 v[96:97], v[80:83], off offset:256
	v_cvt_pk_bf16_f32 v19, v10, v11
	global_store_dwordx4 v[32:33], v[16:19], off offset:256
	s_and_b64 vcc, exec, s[0:1]
	v_lshl_add_u64 v[80:81], v[72:73], 0, v[136:137]
	v_lshl_add_u64 v[16:17], v[8:9], 0, v[136:137]
	s_mov_b32 s83, s81
	s_mov_b32 s84, s82
	s_mov_b64 s[10:11], s[6:7]
	s_mov_b64 s[12:13], s[4:5]
	v_cvt_pk_bf16_f32 v124, v124, v125
	v_cvt_pk_bf16_f32 v125, v126, v127
	v_cvt_pk_bf16_f32 v126, v120, v121
	v_cvt_pk_bf16_f32 v127, v122, v123
	global_store_dwordx4 v[142:143], v[124:127], off
	v_cvt_pk_bf16_f32 v104, v116, v117
	v_cvt_pk_bf16_f32 v105, v118, v119
	v_cvt_pk_bf16_f32 v106, v108, v109
	v_cvt_pk_bf16_f32 v107, v110, v111
	global_store_dwordx4 v[112:113], v[104:107], off
	v_cvt_pk_bf16_f32 v88, v100, v101
	v_cvt_pk_bf16_f32 v89, v102, v103
	v_cvt_pk_bf16_f32 v90, v92, v93
	v_cvt_pk_bf16_f32 v91, v94, v95
	global_store_dwordx4 v[96:97], v[88:91], off
	v_cvt_pk_bf16_f32 v72, v84, v85
	v_cvt_pk_bf16_f32 v73, v86, v87
	v_cvt_pk_bf16_f32 v74, v76, v77
	v_cvt_pk_bf16_f32 v75, v78, v79
	global_store_dwordx4 v[80:81], v[72:75], off
	v_cvt_pk_bf16_f32 v71, v66, v67
	global_store_dwordx4 v[80:81], v[68:71], off offset:256
	v_cvt_pk_bf16_f32 v60, v60, v61
	v_cvt_pk_bf16_f32 v61, v62, v63
	v_cvt_pk_bf16_f32 v62, v56, v57
	v_cvt_pk_bf16_f32 v63, v58, v59
	global_store_dwordx4 v[64:65], v[60:63], off
	v_cvt_pk_bf16_f32 v40, v52, v53
	v_cvt_pk_bf16_f32 v41, v54, v55
	v_cvt_pk_bf16_f32 v42, v44, v45
	v_cvt_pk_bf16_f32 v43, v46, v47
	global_store_dwordx4 v[48:49], v[40:43], off
	v_cvt_pk_bf16_f32 v24, v36, v37
	v_cvt_pk_bf16_f32 v25, v38, v39
	v_cvt_pk_bf16_f32 v26, v28, v29
	v_cvt_pk_bf16_f32 v27, v30, v31
	global_store_dwordx4 v[32:33], v[24:27], off
	v_cvt_pk_bf16_f32 v8, v20, v21
	v_cvt_pk_bf16_f32 v9, v22, v23
	v_cvt_pk_bf16_f32 v10, v12, v13
	v_cvt_pk_bf16_f32 v11, v14, v15
	global_store_dwordx4 v[16:17], v[8:11], off
	v_cvt_pk_bf16_f32 v4, v4, v5
	v_cvt_pk_bf16_f32 v5, v6, v7
	v_cvt_pk_bf16_f32 v6, v0, v1
	v_cvt_pk_bf16_f32 v7, v2, v3
	global_store_dwordx4 v[16:17], v[4:7], off offset:256
	s_cbranch_vccz .LBB0_483
	s_waitcnt vmcnt(0)
	s_cmpk_gt_u32 s34, 0xff
	s_cbranch_scc1 .LBB0_498
	s_barrier
